# dn K-loop: A-operand (H) LDS-DMA loads issued with nt (streamed-once data), test on top of v59
# baseline (speedup 1.0000x reference)
; #define PG8_STAGE(bufoff, gbase, voff) do { _Pragma("unroll") for (int _i = 0; _i < 2; ++_i) \
;         __builtin_amdgcn_global_load_lds((const unsigned*)((const char*)(gbase) + (voff)[_i]), (PG8_LAS unsigned*)(lds + (bufoff) + ldsw + _i * 8192), 16, 0, 0); } while (0)
; #define PG8_LDA(dst, b, h) do { _Pragma("unroll") for (int m = 0; m < 4; ++m) _Pragma("unroll") for (int k = 0; k < 2; ++k) dst[m][k] = *(const PG8_LAS bf16x8*)(lds + PG8_SA(b, h) + aoff + m * 2048 + k * 1024); } while (0)
; #define PG8_LDB(dst, b, h) do { _Pragma("unroll") for (int n = 0; n < 2; ++n) _Pragma("unroll") for (int k = 0; k < 2; ++k) dst[n][k] = *(const PG8_LAS bf16x8*)(lds + PG8_SB(b, h) + boff + n * 2048 + k * 1024); } while (0)
; #define PG8_MMA(ai, bj, At, Bt) do { __builtin_amdgcn_s_setprio(1); _Pragma("unroll") for (int m = 0; m < 4; ++m) _Pragma("unroll") for (int n = 0; n < 2; ++n) _Pragma("unroll") for (int k = 0; k < 2; ++k) \
;         acc[ai][bj][m][n] = __builtin_amdgcn_mfma_f32_16x16x32_bf16(Bt[n][k], At[m][k], acc[ai][bj][m][n], 0, 0, 0); __builtin_amdgcn_s_setprio(0); } while (0)
; #define PG8_WAIT_V(n) asm volatile("s_waitcnt vmcnt(" #n ")" ::: "memory")
; template <class Epi, class Sched, bool ALIGN_EPI = false, bool SP2 = false>
; __device__ __forceinline__ void gemm_phase(PG8_LAS unsigned char* lds, const Gemm g, const Sched& S, const Epi& E) {
;     ...
;             PG8_LDB(B0, 0, 0); PG8_LDB(B1, 0, 1); PG8_SCHED; PG8_LDA(At, 0, 0); PG8_STAGE(PG8_SA(1, 1), a1 + hstep, voffA);
;             PG8_WAIT_V(8); PG8_WAIT_L(0); PG8_BAR; PG8_MMA(0, 0, At, B0); PG8_MMA(0, 1, At, B1); PG8_BAR; PG8_SCHED;
;             PG8_LDA(At, 0, 1); PG8_STAGE(PG8_SB(0, 0), b2, voffB); PG8_STAGE(PG8_SB(0, 1), b2 + hstep, voffB); PG8_STAGE(PG8_SA(0, 0), a2, voffA);
;             PG8_WAIT_V(8); PG8_WAIT_L(0); PG8_BAR; PG8_MMA(1, 0, At, B0); PG8_MMA(1, 1, At, B1); PG8_BAR; PG8_SCHED;
;             PG8_LDB(B0, 1, 0); PG8_LDB(B1, 1, 1); PG8_SCHED; PG8_LDA(At, 1, 0); PG8_STAGE(PG8_SA(0, 1), a2 + hstep, voffA);
;             PG8_WAIT_V(8); PG8_WAIT_L(0); PG8_BAR; PG8_MMA(0, 0, At, B0); PG8_MMA(0, 1, At, B1); PG8_BAR; PG8_SCHED;
;             PG8_LDA(At, 1, 1); PG8_STAGE(PG8_SB(1, 0), b3, voffB); PG8_STAGE(PG8_SB(1, 1), b3 + hstep, voffB); PG8_STAGE(PG8_SA(1, 0), a3, voffA);
;             PG8_WAIT_V(8); PG8_WAIT_L(0); PG8_BAR; PG8_MMA(1, 0, At, B0); PG8_MMA(1, 1, At, B1); PG8_BAR; PG8_SCHED;
.Ldn_peel:
	ds_read_b128 v[128:131], v254
	ds_read_b128 v[132:135], v254 offset:1024
	ds_read_b128 v[136:139], v254 offset:2048
	ds_read_b128 v[140:143], v254 offset:3072
	ds_read_b128 v[174:177], v254 offset:16384
	ds_read_b128 v[184:187], v254 offset:17408
	ds_read_b128 v[188:191], v254 offset:18432
	ds_read_b128 v[210:213], v254 offset:19456
	s_add_u32 s2, s0, 0x100
	s_addc_u32 s3, s1, 0
	s_cmp_eq_u32 s13, 40
	s_cselect_b32 s7, s27, s3
	s_cselect_b32 s6, s26, s2
	s_cselect_b32 s5, s37, s11
	s_cselect_b32 s4, s36, s10
	s_add_i32 m0, s29, 0xc000
	ds_read_b128 v[214:217], v181
	ds_read_b128 v[218:221], v181 offset:1024
	ds_read_b128 v[222:225], v181 offset:2048
	ds_read_b128 v[226:229], v181 offset:3072
	ds_read_b128 v[230:233], v181 offset:4096
	ds_read_b128 v[234:237], v181 offset:5120
	ds_read_b128 v[238:241], v181 offset:6144
	ds_read_b128 v[242:245], v181 offset:7168
	global_load_lds_dwordx4 v170, s[0:1] nt
	s_add_i32 m0, s29, 0xe000
	s_nop 0
	global_load_lds_dwordx4 v172, s[0:1] nt
	s_waitcnt vmcnt(8)
	s_waitcnt lgkmcnt(0)
	s_barrier
	s_setprio 1
	v_mfma_f32_16x16x32_bf16 v[124:127], v[128:131], v[214:217], 0
	v_mfma_f32_16x16x32_bf16 v[120:123], v[136:139], v[214:217], 0
	v_mfma_f32_16x16x32_bf16 v[108:111], v[128:131], v[222:225], 0
	v_mfma_f32_16x16x32_bf16 v[104:107], v[136:139], v[222:225], 0
	v_mfma_f32_16x16x32_bf16 v[92:95], v[128:131], v[230:233], 0
	v_mfma_f32_16x16x32_bf16 v[88:91], v[136:139], v[230:233], 0
	v_mfma_f32_16x16x32_bf16 v[76:79], v[128:131], v[238:241], 0
	v_mfma_f32_16x16x32_bf16 v[72:75], v[136:139], v[238:241], 0
	v_mfma_f32_16x16x32_bf16 v[124:127], v[132:135], v[218:221], v[124:127]
	v_mfma_f32_16x16x32_bf16 v[120:123], v[140:143], v[218:221], v[120:123]
	v_mfma_f32_16x16x32_bf16 v[108:111], v[132:135], v[226:229], v[108:111]
	v_mfma_f32_16x16x32_bf16 v[104:107], v[140:143], v[226:229], v[104:107]
	v_mfma_f32_16x16x32_bf16 v[92:95], v[132:135], v[234:237], v[92:95]
	v_mfma_f32_16x16x32_bf16 v[88:91], v[140:143], v[234:237], v[88:91]
	v_mfma_f32_16x16x32_bf16 v[76:79], v[132:135], v[242:245], v[76:79]
	v_mfma_f32_16x16x32_bf16 v[72:75], v[140:143], v[242:245], v[72:75]
	v_mfma_f32_16x16x32_bf16 v[116:119], v[174:177], v[214:217], 0
	v_mfma_f32_16x16x32_bf16 v[112:115], v[188:191], v[214:217], 0
	v_mfma_f32_16x16x32_bf16 v[100:103], v[174:177], v[222:225], 0
	v_mfma_f32_16x16x32_bf16 v[96:99], v[188:191], v[222:225], 0
	v_mfma_f32_16x16x32_bf16 v[84:87], v[174:177], v[230:233], 0
	v_mfma_f32_16x16x32_bf16 v[80:83], v[188:191], v[230:233], 0
	v_mfma_f32_16x16x32_bf16 v[68:71], v[174:177], v[238:241], 0
	v_mfma_f32_16x16x32_bf16 v[64:67], v[188:191], v[238:241], 0
	v_mfma_f32_16x16x32_bf16 v[116:119], v[184:187], v[218:221], v[116:119]
	v_mfma_f32_16x16x32_bf16 v[112:115], v[210:213], v[218:221], v[112:115]
	v_mfma_f32_16x16x32_bf16 v[100:103], v[184:187], v[226:229], v[100:103]
	v_mfma_f32_16x16x32_bf16 v[96:99], v[210:213], v[226:229], v[96:99]
	v_mfma_f32_16x16x32_bf16 v[84:87], v[184:187], v[234:237], v[84:87]
	v_mfma_f32_16x16x32_bf16 v[80:83], v[210:213], v[234:237], v[80:83]
	v_mfma_f32_16x16x32_bf16 v[68:71], v[184:187], v[242:245], v[68:71]
	v_mfma_f32_16x16x32_bf16 v[64:67], v[210:213], v[242:245], v[64:67]
	s_setprio 0
	s_barrier
	s_mov_b32 m0, s35
	s_add_u32 s0, s4, 0xb0000
	s_addc_u32 s1, s5, 0
	ds_read_b128 v[214:217], v181 offset:16384
	ds_read_b128 v[218:221], v181 offset:17408
	ds_read_b128 v[222:225], v181 offset:18432
	ds_read_b128 v[226:229], v181 offset:19456
	ds_read_b128 v[230:233], v181 offset:20480
	ds_read_b128 v[234:237], v181 offset:21504
	ds_read_b128 v[238:241], v181 offset:22528
	ds_read_b128 v[242:245], v181 offset:23552
	global_load_lds_dwordx4 v166, s[4:5]
	s_mov_b32 m0, s38
	s_nop 0
	global_load_lds_dwordx4 v162, s[4:5]
	s_mov_b32 m0, s39
	s_nop 0
	global_load_lds_dwordx4 v166, s[0:1]
	s_mov_b32 m0, s40
	s_nop 0
	global_load_lds_dwordx4 v162, s[0:1]
	s_mov_b32 m0, s29
	s_nop 0
	global_load_lds_dwordx4 v168, s[6:7] nt
	s_mov_b32 m0, s41
	s_nop 0
	global_load_lds_dwordx4 v164, s[6:7] nt
	s_waitcnt vmcnt(8)
	s_waitcnt lgkmcnt(0)
	s_barrier
	s_setprio 1
	v_mfma_f32_16x16x32_bf16 v[60:63], v[128:131], v[214:217], 0
	v_mfma_f32_16x16x32_bf16 v[56:59], v[136:139], v[214:217], 0
	v_mfma_f32_16x16x32_bf16 v[44:47], v[128:131], v[222:225], 0
	v_mfma_f32_16x16x32_bf16 v[40:43], v[136:139], v[222:225], 0
	v_mfma_f32_16x16x32_bf16 v[28:31], v[128:131], v[230:233], 0
	v_mfma_f32_16x16x32_bf16 v[24:27], v[136:139], v[230:233], 0
	v_mfma_f32_16x16x32_bf16 v[12:15], v[128:131], v[238:241], 0
	v_mfma_f32_16x16x32_bf16 v[8:11], v[136:139], v[238:241], 0
	v_mfma_f32_16x16x32_bf16 v[60:63], v[132:135], v[218:221], v[60:63]
	v_mfma_f32_16x16x32_bf16 v[56:59], v[140:143], v[218:221], v[56:59]
	v_mfma_f32_16x16x32_bf16 v[44:47], v[132:135], v[226:229], v[44:47]
	v_mfma_f32_16x16x32_bf16 v[40:43], v[140:143], v[226:229], v[40:43]
	v_mfma_f32_16x16x32_bf16 v[28:31], v[132:135], v[234:237], v[28:31]
	v_mfma_f32_16x16x32_bf16 v[24:27], v[140:143], v[234:237], v[24:27]
	v_mfma_f32_16x16x32_bf16 v[12:15], v[132:135], v[242:245], v[12:15]
	v_mfma_f32_16x16x32_bf16 v[8:11], v[140:143], v[242:245], v[8:11]
	v_mfma_f32_16x16x32_bf16 v[52:55], v[174:177], v[214:217], 0
	v_mfma_f32_16x16x32_bf16 v[48:51], v[188:191], v[214:217], 0
	v_mfma_f32_16x16x32_bf16 v[36:39], v[174:177], v[222:225], 0
	v_mfma_f32_16x16x32_bf16 v[32:35], v[188:191], v[222:225], 0
	v_mfma_f32_16x16x32_bf16 v[20:23], v[174:177], v[230:233], 0
	v_mfma_f32_16x16x32_bf16 v[16:19], v[188:191], v[230:233], 0
	v_mfma_f32_16x16x32_bf16 v[4:7], v[174:177], v[238:241], 0
	v_mfma_f32_16x16x32_bf16 v[0:3], v[188:191], v[238:241], 0
	v_mfma_f32_16x16x32_bf16 v[52:55], v[184:187], v[218:221], v[52:55]
	v_mfma_f32_16x16x32_bf16 v[48:51], v[210:213], v[218:221], v[48:51]
	v_mfma_f32_16x16x32_bf16 v[36:39], v[184:187], v[226:229], v[36:39]
	v_mfma_f32_16x16x32_bf16 v[32:35], v[210:213], v[226:229], v[32:35]
	v_mfma_f32_16x16x32_bf16 v[20:23], v[184:187], v[234:237], v[20:23]
	v_mfma_f32_16x16x32_bf16 v[16:19], v[210:213], v[234:237], v[16:19]
	v_mfma_f32_16x16x32_bf16 v[4:7], v[184:187], v[242:245], v[4:7]
	v_mfma_f32_16x16x32_bf16 v[0:3], v[210:213], v[242:245], v[0:3]
	s_setprio 0
	s_barrier
; #define PG8_STAGE(bufoff, gbase, voff) do { _Pragma("unroll") for (int _i = 0; _i < 2; ++_i) \
;         __builtin_amdgcn_global_load_lds((const unsigned*)((const char*)(gbase) + (voff)[_i]), (PG8_LAS unsigned*)(lds + (bufoff) + ldsw + _i * 8192), 16, 0, 0); } while (0)
; #define PG8_LDA(dst, b, h) do { _Pragma("unroll") for (int m = 0; m < 4; ++m) _Pragma("unroll") for (int k = 0; k < 2; ++k) dst[m][k] = *(const PG8_LAS bf16x8*)(lds + PG8_SA(b, h) + aoff + m * 2048 + k * 1024); } while (0)
; #define PG8_LDB(dst, b, h) do { _Pragma("unroll") for (int n = 0; n < 2; ++n) _Pragma("unroll") for (int k = 0; k < 2; ++k) dst[n][k] = *(const PG8_LAS bf16x8*)(lds + PG8_SB(b, h) + boff + n * 2048 + k * 1024); } while (0)
; #define PG8_MMA(ai, bj, At, Bt) do { __builtin_amdgcn_s_setprio(1); _Pragma("unroll") for (int m = 0; m < 4; ++m) _Pragma("unroll") for (int n = 0; n < 2; ++n) _Pragma("unroll") for (int k = 0; k < 2; ++k) \
;         acc[ai][bj][m][n] = __builtin_amdgcn_mfma_f32_16x16x32_bf16(Bt[n][k], At[m][k], acc[ai][bj][m][n], 0, 0, 0); __builtin_amdgcn_s_setprio(0); } while (0)
; #define PG8_WAIT_V(n) asm volatile("s_waitcnt vmcnt(" #n ")" ::: "memory")
; #define PG8_WAIT_L(n) asm volatile("s_waitcnt lgkmcnt(" #n ")" ::: "memory")
; #define PG8_BAR __builtin_amdgcn_s_barrier()
; #define PG8_SCHED __builtin_amdgcn_sched_barrier(0)
; template <class Epi, class Sched, bool ALIGN_EPI = false, bool SP2 = false>
; __device__ __forceinline__ void gemm_phase(PG8_LAS unsigned char* lds, const Gemm g, const Sched& S, const Epi& E) {
;     ...
;             PG8_LDB(B0, 1, 0); PG8_LDB(B1, 1, 1); PG8_SCHED; PG8_LDA(At, 1, 0); PG8_STAGE(PG8_SA(0, 1), a2 + hstep, voffA);
;             PG8_WAIT_V(8); PG8_WAIT_L(0); PG8_BAR; PG8_MMA(0, 0, At, B0); PG8_MMA(0, 1, At, B1); PG8_BAR; PG8_SCHED;
;             PG8_LDA(At, 1, 1); PG8_STAGE(PG8_SB(1, 0), b3, voffB); PG8_STAGE(PG8_SB(1, 1), b3 + hstep, voffB); PG8_STAGE(PG8_SA(1, 0), a3, voffA);
;             PG8_WAIT_V(8); PG8_WAIT_L(0); PG8_BAR; PG8_MMA(1, 0, At, B0); PG8_MMA(1, 1, At, B1); PG8_BAR; PG8_SCHED;
	ds_read_b128 v[128:131], v254 offset:32768
	ds_read_b128 v[132:135], v254 offset:33792
	ds_read_b128 v[136:139], v254 offset:34816
	ds_read_b128 v[140:143], v254 offset:35840
	ds_read_b128 v[174:177], v254 offset:49152
	ds_read_b128 v[184:187], v254 offset:50176
	ds_read_b128 v[188:191], v254 offset:51200
	ds_read_b128 v[210:213], v254 offset:52224
	s_add_u32 s0, s6, 0xb0000
	s_addc_u32 s1, s7, 0
	s_mov_b32 m0, s42
	ds_read_b128 v[214:217], v181 offset:32768
	ds_read_b128 v[218:221], v181 offset:33792
	ds_read_b128 v[222:225], v181 offset:34816
	ds_read_b128 v[226:229], v181 offset:35840
	ds_read_b128 v[230:233], v181 offset:36864
	ds_read_b128 v[234:237], v181 offset:37888
	ds_read_b128 v[238:241], v181 offset:38912
	ds_read_b128 v[242:245], v181 offset:39936
	global_load_lds_dwordx4 v168, s[0:1] nt
	s_mov_b32 m0, s43
	s_nop 0
	global_load_lds_dwordx4 v164, s[0:1] nt
	s_waitcnt vmcnt(8)
	s_waitcnt lgkmcnt(0)
	s_barrier
	s_setprio 1
	v_mfma_f32_16x16x32_bf16 v[124:127], v[128:131], v[214:217], v[124:127]
	v_mfma_f32_16x16x32_bf16 v[120:123], v[136:139], v[214:217], v[120:123]
	v_mfma_f32_16x16x32_bf16 v[108:111], v[128:131], v[222:225], v[108:111]
	v_mfma_f32_16x16x32_bf16 v[104:107], v[136:139], v[222:225], v[104:107]
	v_mfma_f32_16x16x32_bf16 v[92:95], v[128:131], v[230:233], v[92:95]
	v_mfma_f32_16x16x32_bf16 v[88:91], v[136:139], v[230:233], v[88:91]
	v_mfma_f32_16x16x32_bf16 v[76:79], v[128:131], v[238:241], v[76:79]
	v_mfma_f32_16x16x32_bf16 v[72:75], v[136:139], v[238:241], v[72:75]
	v_mfma_f32_16x16x32_bf16 v[124:127], v[132:135], v[218:221], v[124:127]
	v_mfma_f32_16x16x32_bf16 v[120:123], v[140:143], v[218:221], v[120:123]
	v_mfma_f32_16x16x32_bf16 v[108:111], v[132:135], v[226:229], v[108:111]
	v_mfma_f32_16x16x32_bf16 v[104:107], v[140:143], v[226:229], v[104:107]
	v_mfma_f32_16x16x32_bf16 v[92:95], v[132:135], v[234:237], v[92:95]
	v_mfma_f32_16x16x32_bf16 v[88:91], v[140:143], v[234:237], v[88:91]
	v_mfma_f32_16x16x32_bf16 v[76:79], v[132:135], v[242:245], v[76:79]
	v_mfma_f32_16x16x32_bf16 v[72:75], v[140:143], v[242:245], v[72:75]
	v_mfma_f32_16x16x32_bf16 v[116:119], v[174:177], v[214:217], v[116:119]
	v_mfma_f32_16x16x32_bf16 v[112:115], v[188:191], v[214:217], v[112:115]
	v_mfma_f32_16x16x32_bf16 v[100:103], v[174:177], v[222:225], v[100:103]
	v_mfma_f32_16x16x32_bf16 v[96:99], v[188:191], v[222:225], v[96:99]
	v_mfma_f32_16x16x32_bf16 v[84:87], v[174:177], v[230:233], v[84:87]
	v_mfma_f32_16x16x32_bf16 v[80:83], v[188:191], v[230:233], v[80:83]
	v_mfma_f32_16x16x32_bf16 v[68:71], v[174:177], v[238:241], v[68:71]
	v_mfma_f32_16x16x32_bf16 v[64:67], v[188:191], v[238:241], v[64:67]
	v_mfma_f32_16x16x32_bf16 v[116:119], v[184:187], v[218:221], v[116:119]
	v_mfma_f32_16x16x32_bf16 v[112:115], v[210:213], v[218:221], v[112:115]
	v_mfma_f32_16x16x32_bf16 v[100:103], v[184:187], v[226:229], v[100:103]
	v_mfma_f32_16x16x32_bf16 v[96:99], v[210:213], v[226:229], v[96:99]
	v_mfma_f32_16x16x32_bf16 v[84:87], v[184:187], v[234:237], v[84:87]
	v_mfma_f32_16x16x32_bf16 v[80:83], v[210:213], v[234:237], v[80:83]
	v_mfma_f32_16x16x32_bf16 v[68:71], v[184:187], v[242:245], v[68:71]
	v_mfma_f32_16x16x32_bf16 v[64:67], v[210:213], v[242:245], v[64:67]
	s_setprio 0
	s_barrier
	s_mov_b32 m0, s47
	s_add_u32 s0, s4, 0xb0080
	s_addc_u32 s1, s5, 0
	ds_read_b128 v[214:217], v181 offset:49152
	ds_read_b128 v[218:221], v181 offset:50176
	ds_read_b128 v[222:225], v181 offset:51200
	ds_read_b128 v[226:229], v181 offset:52224
	ds_read_b128 v[230:233], v181 offset:53248
	ds_read_b128 v[234:237], v181 offset:54272
	ds_read_b128 v[238:241], v181 offset:55296
	ds_read_b128 v[242:245], v181 offset:56320
	s_add_u32 s98, s4, 0x80
	s_addc_u32 s99, s5, 0
	global_load_lds_dwordx4 v166, s[98:99]
	s_mov_b32 m0, s48
	s_nop 0
	global_load_lds_dwordx4 v162, s[98:99]
	s_mov_b32 m0, s51
	s_nop 0
	global_load_lds_dwordx4 v166, s[0:1]
	s_mov_b32 m0, s52
	s_nop 0
	global_load_lds_dwordx4 v162, s[0:1]
	s_mov_b32 m0, s49
	s_nop 0
	s_add_u32 s100, s6, 0x80
	s_addc_u32 s101, s7, 0
	global_load_lds_dwordx4 v168, s[100:101] nt
	s_mov_b32 m0, s50
	s_nop 0
	global_load_lds_dwordx4 v164, s[100:101] nt
	s_waitcnt vmcnt(8)
	s_waitcnt lgkmcnt(0)
	s_barrier
	s_setprio 1
	v_mfma_f32_16x16x32_bf16 v[60:63], v[128:131], v[214:217], v[60:63]
	v_mfma_f32_16x16x32_bf16 v[56:59], v[136:139], v[214:217], v[56:59]
	v_mfma_f32_16x16x32_bf16 v[44:47], v[128:131], v[222:225], v[44:47]
	v_mfma_f32_16x16x32_bf16 v[40:43], v[136:139], v[222:225], v[40:43]
	v_mfma_f32_16x16x32_bf16 v[28:31], v[128:131], v[230:233], v[28:31]
	v_mfma_f32_16x16x32_bf16 v[24:27], v[136:139], v[230:233], v[24:27]
	v_mfma_f32_16x16x32_bf16 v[12:15], v[128:131], v[238:241], v[12:15]
	v_mfma_f32_16x16x32_bf16 v[8:11], v[136:139], v[238:241], v[8:11]
	v_mfma_f32_16x16x32_bf16 v[60:63], v[132:135], v[218:221], v[60:63]
	v_mfma_f32_16x16x32_bf16 v[56:59], v[140:143], v[218:221], v[56:59]
	v_mfma_f32_16x16x32_bf16 v[44:47], v[132:135], v[226:229], v[44:47]
	v_mfma_f32_16x16x32_bf16 v[40:43], v[140:143], v[226:229], v[40:43]
	v_mfma_f32_16x16x32_bf16 v[28:31], v[132:135], v[234:237], v[28:31]
	v_mfma_f32_16x16x32_bf16 v[24:27], v[140:143], v[234:237], v[24:27]
	v_mfma_f32_16x16x32_bf16 v[12:15], v[132:135], v[242:245], v[12:15]
	v_mfma_f32_16x16x32_bf16 v[8:11], v[140:143], v[242:245], v[8:11]
	v_mfma_f32_16x16x32_bf16 v[52:55], v[174:177], v[214:217], v[52:55]
	v_mfma_f32_16x16x32_bf16 v[48:51], v[188:191], v[214:217], v[48:51]
	v_mfma_f32_16x16x32_bf16 v[36:39], v[174:177], v[222:225], v[36:39]
	v_mfma_f32_16x16x32_bf16 v[32:35], v[188:191], v[222:225], v[32:35]
	v_mfma_f32_16x16x32_bf16 v[20:23], v[174:177], v[230:233], v[20:23]
	v_mfma_f32_16x16x32_bf16 v[16:19], v[188:191], v[230:233], v[16:19]
	v_mfma_f32_16x16x32_bf16 v[4:7], v[174:177], v[238:241], v[4:7]
	v_mfma_f32_16x16x32_bf16 v[0:3], v[188:191], v[238:241], v[0:3]
	v_mfma_f32_16x16x32_bf16 v[52:55], v[184:187], v[218:221], v[52:55]
	v_mfma_f32_16x16x32_bf16 v[48:51], v[210:213], v[218:221], v[48:51]
	v_mfma_f32_16x16x32_bf16 v[36:39], v[184:187], v[226:229], v[36:39]
	v_mfma_f32_16x16x32_bf16 v[32:35], v[210:213], v[226:229], v[32:35]
	v_mfma_f32_16x16x32_bf16 v[20:23], v[184:187], v[234:237], v[20:23]
	v_mfma_f32_16x16x32_bf16 v[16:19], v[210:213], v[234:237], v[16:19]
	v_mfma_f32_16x16x32_bf16 v[4:7], v[184:187], v[242:245], v[4:7]
	v_mfma_f32_16x16x32_bf16 v[0:3], v[210:213], v[242:245], v[0:3]
	s_setprio 0
	s_barrier
	s_add_i32 s13, s13, 2
	s_add_u32 s10, s10, 0x100
	s_addc_u32 s11, s11, 0
	s_cmp_gt_u32 s13, 41
	s_mov_b64 s[0:1], s[2:3]
; #define PG8_STAGE(bufoff, gbase, voff) do { _Pragma("unroll") for (int _i = 0; _i < 2; ++_i) \
;         __builtin_amdgcn_global_load_lds((const unsigned*)((const char*)(gbase) + (voff)[_i]), (PG8_LAS unsigned*)(lds + (bufoff) + ldsw + _i * 8192), 16, 0, 0); } while (0)
; #define PG8_LDA(dst, b, h) do { _Pragma("unroll") for (int m = 0; m < 4; ++m) _Pragma("unroll") for (int k = 0; k < 2; ++k) dst[m][k] = *(const PG8_LAS bf16x8*)(lds + PG8_SA(b, h) + aoff + m * 2048 + k * 1024); } while (0)
; #define PG8_LDB(dst, b, h) do { _Pragma("unroll") for (int n = 0; n < 2; ++n) _Pragma("unroll") for (int k = 0; k < 2; ++k) dst[n][k] = *(const PG8_LAS bf16x8*)(lds + PG8_SB(b, h) + boff + n * 2048 + k * 1024); } while (0)
; #define PG8_MMA(ai, bj, At, Bt) do { __builtin_amdgcn_s_setprio(1); _Pragma("unroll") for (int m = 0; m < 4; ++m) _Pragma("unroll") for (int n = 0; n < 2; ++n) _Pragma("unroll") for (int k = 0; k < 2; ++k) \
;         acc[ai][bj][m][n] = __builtin_amdgcn_mfma_f32_16x16x32_bf16(Bt[n][k], At[m][k], acc[ai][bj][m][n], 0, 0, 0); __builtin_amdgcn_s_setprio(0); } while (0)
; #define PG8_WAIT_V(n) asm volatile("s_waitcnt vmcnt(" #n ")" ::: "memory")
; #define PG8_WAIT_L(n) asm volatile("s_waitcnt lgkmcnt(" #n ")" ::: "memory")
; #define PG8_BAR __builtin_amdgcn_s_barrier()
; #define PG8_SCHED __builtin_amdgcn_sched_barrier(0)
; template <class Epi, class Sched, bool ALIGN_EPI = false, bool SP2 = false>
; __device__ __forceinline__ void gemm_phase(PG8_LAS unsigned char* lds, const Gemm g, const Sched& S, const Epi& E) {
;     ...
;             PG8_LDB(B0, 0, 0); PG8_LDB(B1, 0, 1); PG8_SCHED; PG8_LDA(At, 0, 0); PG8_STAGE(PG8_SA(1, 1), a1 + hstep, voffA);
;             PG8_WAIT_V(8); PG8_WAIT_L(0); PG8_BAR; PG8_MMA(0, 0, At, B0); PG8_MMA(0, 1, At, B1); PG8_BAR; PG8_SCHED;
;             PG8_LDA(At, 0, 1); PG8_STAGE(PG8_SB(0, 0), b2, voffB); PG8_STAGE(PG8_SB(0, 1), b2 + hstep, voffB); PG8_STAGE(PG8_SA(0, 0), a2, voffA);
;             PG8_WAIT_V(8); PG8_WAIT_L(0); PG8_BAR; PG8_MMA(1, 0, At, B0); PG8_MMA(1, 1, At, B1); PG8_BAR; PG8_SCHED;
.LBB0_545:
	ds_read_b128 v[128:131], v254
	ds_read_b128 v[132:135], v254 offset:1024
	ds_read_b128 v[136:139], v254 offset:2048
	ds_read_b128 v[140:143], v254 offset:3072
	ds_read_b128 v[174:177], v254 offset:16384
	ds_read_b128 v[184:187], v254 offset:17408
	ds_read_b128 v[188:191], v254 offset:18432
	ds_read_b128 v[210:213], v254 offset:19456
	s_add_u32 s2, s0, 0x100
	s_addc_u32 s3, s1, 0
	s_cmp_eq_u32 s13, 40
	s_cselect_b32 s7, s27, s3
	s_cselect_b32 s6, s26, s2
	s_cselect_b32 s5, s37, s11
	s_cselect_b32 s4, s36, s10
	s_add_i32 m0, s29, 0xc000
	ds_read_b128 v[214:217], v181
	ds_read_b128 v[218:221], v181 offset:1024
	ds_read_b128 v[222:225], v181 offset:2048
	ds_read_b128 v[226:229], v181 offset:3072
	ds_read_b128 v[230:233], v181 offset:4096
	ds_read_b128 v[234:237], v181 offset:5120
	ds_read_b128 v[238:241], v181 offset:6144
	ds_read_b128 v[242:245], v181 offset:7168
	global_load_lds_dwordx4 v170, s[0:1] nt
	s_add_i32 m0, s29, 0xe000
	s_nop 0
	global_load_lds_dwordx4 v172, s[0:1] nt
	s_waitcnt vmcnt(8)
	s_waitcnt lgkmcnt(0)
	s_barrier
	s_setprio 1
	v_mfma_f32_16x16x32_bf16 v[124:127], v[128:131], v[214:217], v[124:127]
	v_mfma_f32_16x16x32_bf16 v[120:123], v[136:139], v[214:217], v[120:123]
	v_mfma_f32_16x16x32_bf16 v[108:111], v[128:131], v[222:225], v[108:111]
	v_mfma_f32_16x16x32_bf16 v[104:107], v[136:139], v[222:225], v[104:107]
	v_mfma_f32_16x16x32_bf16 v[92:95], v[128:131], v[230:233], v[92:95]
	v_mfma_f32_16x16x32_bf16 v[88:91], v[136:139], v[230:233], v[88:91]
	v_mfma_f32_16x16x32_bf16 v[76:79], v[128:131], v[238:241], v[76:79]
	v_mfma_f32_16x16x32_bf16 v[72:75], v[136:139], v[238:241], v[72:75]
	v_mfma_f32_16x16x32_bf16 v[124:127], v[132:135], v[218:221], v[124:127]
	v_mfma_f32_16x16x32_bf16 v[120:123], v[140:143], v[218:221], v[120:123]
	v_mfma_f32_16x16x32_bf16 v[108:111], v[132:135], v[226:229], v[108:111]
	v_mfma_f32_16x16x32_bf16 v[104:107], v[140:143], v[226:229], v[104:107]
	v_mfma_f32_16x16x32_bf16 v[92:95], v[132:135], v[234:237], v[92:95]
	v_mfma_f32_16x16x32_bf16 v[88:91], v[140:143], v[234:237], v[88:91]
	v_mfma_f32_16x16x32_bf16 v[76:79], v[132:135], v[242:245], v[76:79]
	v_mfma_f32_16x16x32_bf16 v[72:75], v[140:143], v[242:245], v[72:75]
	v_mfma_f32_16x16x32_bf16 v[116:119], v[174:177], v[214:217], v[116:119]
	v_mfma_f32_16x16x32_bf16 v[112:115], v[188:191], v[214:217], v[112:115]
	v_mfma_f32_16x16x32_bf16 v[100:103], v[174:177], v[222:225], v[100:103]
	v_mfma_f32_16x16x32_bf16 v[96:99], v[188:191], v[222:225], v[96:99]
	v_mfma_f32_16x16x32_bf16 v[84:87], v[174:177], v[230:233], v[84:87]
	v_mfma_f32_16x16x32_bf16 v[80:83], v[188:191], v[230:233], v[80:83]
	v_mfma_f32_16x16x32_bf16 v[68:71], v[174:177], v[238:241], v[68:71]
	v_mfma_f32_16x16x32_bf16 v[64:67], v[188:191], v[238:241], v[64:67]
	v_mfma_f32_16x16x32_bf16 v[116:119], v[184:187], v[218:221], v[116:119]
	v_mfma_f32_16x16x32_bf16 v[112:115], v[210:213], v[218:221], v[112:115]
	v_mfma_f32_16x16x32_bf16 v[100:103], v[184:187], v[226:229], v[100:103]
	v_mfma_f32_16x16x32_bf16 v[96:99], v[210:213], v[226:229], v[96:99]
	v_mfma_f32_16x16x32_bf16 v[84:87], v[184:187], v[234:237], v[84:87]
	v_mfma_f32_16x16x32_bf16 v[80:83], v[210:213], v[234:237], v[80:83]
	v_mfma_f32_16x16x32_bf16 v[68:71], v[184:187], v[242:245], v[68:71]
	v_mfma_f32_16x16x32_bf16 v[64:67], v[210:213], v[242:245], v[64:67]
	s_setprio 0
	s_barrier
	s_mov_b32 m0, s35
	s_add_u32 s0, s4, 0xb0000
	s_addc_u32 s1, s5, 0
	ds_read_b128 v[214:217], v181 offset:16384
	ds_read_b128 v[218:221], v181 offset:17408
	ds_read_b128 v[222:225], v181 offset:18432
	ds_read_b128 v[226:229], v181 offset:19456
	ds_read_b128 v[230:233], v181 offset:20480
	ds_read_b128 v[234:237], v181 offset:21504
	ds_read_b128 v[238:241], v181 offset:22528
	ds_read_b128 v[242:245], v181 offset:23552
	global_load_lds_dwordx4 v166, s[4:5]
	s_mov_b32 m0, s38
	s_nop 0
	global_load_lds_dwordx4 v162, s[4:5]
	s_mov_b32 m0, s39
	s_nop 0
	global_load_lds_dwordx4 v166, s[0:1]
	s_mov_b32 m0, s40
	s_nop 0
	global_load_lds_dwordx4 v162, s[0:1]
	s_mov_b32 m0, s29
	s_nop 0
	global_load_lds_dwordx4 v168, s[6:7] nt
	s_mov_b32 m0, s41
	s_nop 0
	global_load_lds_dwordx4 v164, s[6:7] nt
	s_waitcnt vmcnt(8)
	s_waitcnt lgkmcnt(0)
	s_barrier
	s_setprio 1
	v_mfma_f32_16x16x32_bf16 v[60:63], v[128:131], v[214:217], v[60:63]
	v_mfma_f32_16x16x32_bf16 v[56:59], v[136:139], v[214:217], v[56:59]
	v_mfma_f32_16x16x32_bf16 v[44:47], v[128:131], v[222:225], v[44:47]
	v_mfma_f32_16x16x32_bf16 v[40:43], v[136:139], v[222:225], v[40:43]
	v_mfma_f32_16x16x32_bf16 v[28:31], v[128:131], v[230:233], v[28:31]
	v_mfma_f32_16x16x32_bf16 v[24:27], v[136:139], v[230:233], v[24:27]
	v_mfma_f32_16x16x32_bf16 v[12:15], v[128:131], v[238:241], v[12:15]
	v_mfma_f32_16x16x32_bf16 v[8:11], v[136:139], v[238:241], v[8:11]
	v_mfma_f32_16x16x32_bf16 v[60:63], v[132:135], v[218:221], v[60:63]
	v_mfma_f32_16x16x32_bf16 v[56:59], v[140:143], v[218:221], v[56:59]
	v_mfma_f32_16x16x32_bf16 v[44:47], v[132:135], v[226:229], v[44:47]
	v_mfma_f32_16x16x32_bf16 v[40:43], v[140:143], v[226:229], v[40:43]
	v_mfma_f32_16x16x32_bf16 v[28:31], v[132:135], v[234:237], v[28:31]
	v_mfma_f32_16x16x32_bf16 v[24:27], v[140:143], v[234:237], v[24:27]
	v_mfma_f32_16x16x32_bf16 v[12:15], v[132:135], v[242:245], v[12:15]
	v_mfma_f32_16x16x32_bf16 v[8:11], v[140:143], v[242:245], v[8:11]
	v_mfma_f32_16x16x32_bf16 v[52:55], v[174:177], v[214:217], v[52:55]
	v_mfma_f32_16x16x32_bf16 v[48:51], v[188:191], v[214:217], v[48:51]
	v_mfma_f32_16x16x32_bf16 v[36:39], v[174:177], v[222:225], v[36:39]
	v_mfma_f32_16x16x32_bf16 v[32:35], v[188:191], v[222:225], v[32:35]
	v_mfma_f32_16x16x32_bf16 v[20:23], v[174:177], v[230:233], v[20:23]
	v_mfma_f32_16x16x32_bf16 v[16:19], v[188:191], v[230:233], v[16:19]
	v_mfma_f32_16x16x32_bf16 v[4:7], v[174:177], v[238:241], v[4:7]
	v_mfma_f32_16x16x32_bf16 v[0:3], v[188:191], v[238:241], v[0:3]
	v_mfma_f32_16x16x32_bf16 v[52:55], v[184:187], v[218:221], v[52:55]
	v_mfma_f32_16x16x32_bf16 v[48:51], v[210:213], v[218:221], v[48:51]
	v_mfma_f32_16x16x32_bf16 v[36:39], v[184:187], v[226:229], v[36:39]
	v_mfma_f32_16x16x32_bf16 v[32:35], v[210:213], v[226:229], v[32:35]
	v_mfma_f32_16x16x32_bf16 v[20:23], v[184:187], v[234:237], v[20:23]
	v_mfma_f32_16x16x32_bf16 v[16:19], v[210:213], v[234:237], v[16:19]
	v_mfma_f32_16x16x32_bf16 v[4:7], v[184:187], v[242:245], v[4:7]
	v_mfma_f32_16x16x32_bf16 v[0:3], v[210:213], v[242:245], v[0:3]
	s_setprio 0
	s_barrier
; #define PG8_STAGE(bufoff, gbase, voff) do { _Pragma("unroll") for (int _i = 0; _i < 2; ++_i) \
;         __builtin_amdgcn_global_load_lds((const unsigned*)((const char*)(gbase) + (voff)[_i]), (PG8_LAS unsigned*)(lds + (bufoff) + ldsw + _i * 8192), 16, 0, 0); } while (0)
; #define PG8_LDA(dst, b, h) do { _Pragma("unroll") for (int m = 0; m < 4; ++m) _Pragma("unroll") for (int k = 0; k < 2; ++k) dst[m][k] = *(const PG8_LAS bf16x8*)(lds + PG8_SA(b, h) + aoff + m * 2048 + k * 1024); } while (0)
; #define PG8_LDB(dst, b, h) do { _Pragma("unroll") for (int n = 0; n < 2; ++n) _Pragma("unroll") for (int k = 0; k < 2; ++k) dst[n][k] = *(const PG8_LAS bf16x8*)(lds + PG8_SB(b, h) + boff + n * 2048 + k * 1024); } while (0)
; #define PG8_MMA(ai, bj, At, Bt) do { __builtin_amdgcn_s_setprio(1); _Pragma("unroll") for (int m = 0; m < 4; ++m) _Pragma("unroll") for (int n = 0; n < 2; ++n) _Pragma("unroll") for (int k = 0; k < 2; ++k) \
;         acc[ai][bj][m][n] = __builtin_amdgcn_mfma_f32_16x16x32_bf16(Bt[n][k], At[m][k], acc[ai][bj][m][n], 0, 0, 0); __builtin_amdgcn_s_setprio(0); } while (0)
; #define PG8_WAIT_V(n) asm volatile("s_waitcnt vmcnt(" #n ")" ::: "memory")
; #define PG8_WAIT_L(n) asm volatile("s_waitcnt lgkmcnt(" #n ")" ::: "memory")
; #define PG8_BAR __builtin_amdgcn_s_barrier()
; #define PG8_SCHED __builtin_amdgcn_sched_barrier(0)
; template <class Epi, class Sched, bool ALIGN_EPI = false, bool SP2 = false>
; __device__ __forceinline__ void gemm_phase(PG8_LAS unsigned char* lds, const Gemm g, const Sched& S, const Epi& E) {
;     ...
;             PG8_LDB(B0, 1, 0); PG8_LDB(B1, 1, 1); PG8_SCHED; PG8_LDA(At, 1, 0); PG8_STAGE(PG8_SA(0, 1), a2 + hstep, voffA);
;             PG8_WAIT_V(8); PG8_WAIT_L(0); PG8_BAR; PG8_MMA(0, 0, At, B0); PG8_MMA(0, 1, At, B1); PG8_BAR; PG8_SCHED;
;             PG8_LDA(At, 1, 1); PG8_STAGE(PG8_SB(1, 0), b3, voffB); PG8_STAGE(PG8_SB(1, 1), b3 + hstep, voffB); PG8_STAGE(PG8_SA(1, 0), a3, voffA);
;             PG8_WAIT_V(8); PG8_WAIT_L(0); PG8_BAR; PG8_MMA(1, 0, At, B0); PG8_MMA(1, 1, At, B1); PG8_BAR; PG8_SCHED;
;     ...
;         if constexpr (ALIGN_EPI) { if (wr == 0) PG8_BAR; }
	ds_read_b128 v[128:131], v254 offset:32768
	ds_read_b128 v[132:135], v254 offset:33792
	ds_read_b128 v[136:139], v254 offset:34816
	ds_read_b128 v[140:143], v254 offset:35840
	ds_read_b128 v[174:177], v254 offset:49152
	ds_read_b128 v[184:187], v254 offset:50176
	ds_read_b128 v[188:191], v254 offset:51200
	ds_read_b128 v[210:213], v254 offset:52224
	s_add_u32 s0, s6, 0xb0000
	s_addc_u32 s1, s7, 0
	s_mov_b32 m0, s42
	ds_read_b128 v[214:217], v181 offset:32768
	ds_read_b128 v[218:221], v181 offset:33792
	ds_read_b128 v[222:225], v181 offset:34816
	ds_read_b128 v[226:229], v181 offset:35840
	ds_read_b128 v[230:233], v181 offset:36864
	ds_read_b128 v[234:237], v181 offset:37888
	ds_read_b128 v[238:241], v181 offset:38912
	ds_read_b128 v[242:245], v181 offset:39936
	global_load_lds_dwordx4 v168, s[0:1] nt
	s_mov_b32 m0, s43
	s_nop 0
	global_load_lds_dwordx4 v164, s[0:1] nt
	s_waitcnt vmcnt(8)
	s_waitcnt lgkmcnt(0)
	s_barrier
	s_setprio 1
	v_mfma_f32_16x16x32_bf16 v[124:127], v[128:131], v[214:217], v[124:127]
	v_mfma_f32_16x16x32_bf16 v[120:123], v[136:139], v[214:217], v[120:123]
	v_mfma_f32_16x16x32_bf16 v[108:111], v[128:131], v[222:225], v[108:111]
	v_mfma_f32_16x16x32_bf16 v[104:107], v[136:139], v[222:225], v[104:107]
	v_mfma_f32_16x16x32_bf16 v[92:95], v[128:131], v[230:233], v[92:95]
	v_mfma_f32_16x16x32_bf16 v[88:91], v[136:139], v[230:233], v[88:91]
	v_mfma_f32_16x16x32_bf16 v[76:79], v[128:131], v[238:241], v[76:79]
	v_mfma_f32_16x16x32_bf16 v[72:75], v[136:139], v[238:241], v[72:75]
	v_mfma_f32_16x16x32_bf16 v[124:127], v[132:135], v[218:221], v[124:127]
	v_mfma_f32_16x16x32_bf16 v[120:123], v[140:143], v[218:221], v[120:123]
	v_mfma_f32_16x16x32_bf16 v[108:111], v[132:135], v[226:229], v[108:111]
	v_mfma_f32_16x16x32_bf16 v[104:107], v[140:143], v[226:229], v[104:107]
	v_mfma_f32_16x16x32_bf16 v[92:95], v[132:135], v[234:237], v[92:95]
	v_mfma_f32_16x16x32_bf16 v[88:91], v[140:143], v[234:237], v[88:91]
	v_mfma_f32_16x16x32_bf16 v[76:79], v[132:135], v[242:245], v[76:79]
	v_mfma_f32_16x16x32_bf16 v[72:75], v[140:143], v[242:245], v[72:75]
	v_mfma_f32_16x16x32_bf16 v[116:119], v[174:177], v[214:217], v[116:119]
	v_mfma_f32_16x16x32_bf16 v[112:115], v[188:191], v[214:217], v[112:115]
	v_mfma_f32_16x16x32_bf16 v[100:103], v[174:177], v[222:225], v[100:103]
	v_mfma_f32_16x16x32_bf16 v[96:99], v[188:191], v[222:225], v[96:99]
	v_mfma_f32_16x16x32_bf16 v[84:87], v[174:177], v[230:233], v[84:87]
	v_mfma_f32_16x16x32_bf16 v[80:83], v[188:191], v[230:233], v[80:83]
	v_mfma_f32_16x16x32_bf16 v[68:71], v[174:177], v[238:241], v[68:71]
	v_mfma_f32_16x16x32_bf16 v[64:67], v[188:191], v[238:241], v[64:67]
	v_mfma_f32_16x16x32_bf16 v[116:119], v[184:187], v[218:221], v[116:119]
	v_mfma_f32_16x16x32_bf16 v[112:115], v[210:213], v[218:221], v[112:115]
	v_mfma_f32_16x16x32_bf16 v[100:103], v[184:187], v[226:229], v[100:103]
	v_mfma_f32_16x16x32_bf16 v[96:99], v[210:213], v[226:229], v[96:99]
	v_mfma_f32_16x16x32_bf16 v[84:87], v[184:187], v[234:237], v[84:87]
	v_mfma_f32_16x16x32_bf16 v[80:83], v[210:213], v[234:237], v[80:83]
	v_mfma_f32_16x16x32_bf16 v[68:71], v[184:187], v[242:245], v[68:71]
	v_mfma_f32_16x16x32_bf16 v[64:67], v[210:213], v[242:245], v[64:67]
	s_setprio 0
	s_barrier
	s_mov_b32 m0, s47
	s_add_u32 s0, s4, 0xb0080
	s_addc_u32 s1, s5, 0
	ds_read_b128 v[214:217], v181 offset:49152
	ds_read_b128 v[218:221], v181 offset:50176
	ds_read_b128 v[222:225], v181 offset:51200
	ds_read_b128 v[226:229], v181 offset:52224
	ds_read_b128 v[230:233], v181 offset:53248
	ds_read_b128 v[234:237], v181 offset:54272
	ds_read_b128 v[238:241], v181 offset:55296
	ds_read_b128 v[242:245], v181 offset:56320
	s_add_u32 s98, s4, 0x80
	s_addc_u32 s99, s5, 0
	global_load_lds_dwordx4 v166, s[98:99]
	s_mov_b32 m0, s48
	s_nop 0
	global_load_lds_dwordx4 v162, s[98:99]
	s_mov_b32 m0, s51
	s_nop 0
	global_load_lds_dwordx4 v166, s[0:1]
	s_mov_b32 m0, s52
	s_nop 0
	global_load_lds_dwordx4 v162, s[0:1]
	s_mov_b32 m0, s49
	s_nop 0
	s_add_u32 s100, s6, 0x80
	s_addc_u32 s101, s7, 0
	global_load_lds_dwordx4 v168, s[100:101] nt
	s_mov_b32 m0, s50
	s_nop 0
	global_load_lds_dwordx4 v164, s[100:101] nt
	s_waitcnt vmcnt(8)
	s_waitcnt lgkmcnt(0)
	s_barrier
	s_setprio 1
	v_mfma_f32_16x16x32_bf16 v[60:63], v[128:131], v[214:217], v[60:63]
	v_mfma_f32_16x16x32_bf16 v[56:59], v[136:139], v[214:217], v[56:59]
	v_mfma_f32_16x16x32_bf16 v[44:47], v[128:131], v[222:225], v[44:47]
	v_mfma_f32_16x16x32_bf16 v[40:43], v[136:139], v[222:225], v[40:43]
	v_mfma_f32_16x16x32_bf16 v[28:31], v[128:131], v[230:233], v[28:31]
	v_mfma_f32_16x16x32_bf16 v[24:27], v[136:139], v[230:233], v[24:27]
	v_mfma_f32_16x16x32_bf16 v[12:15], v[128:131], v[238:241], v[12:15]
	v_mfma_f32_16x16x32_bf16 v[8:11], v[136:139], v[238:241], v[8:11]
	v_mfma_f32_16x16x32_bf16 v[60:63], v[132:135], v[218:221], v[60:63]
	v_mfma_f32_16x16x32_bf16 v[56:59], v[140:143], v[218:221], v[56:59]
	v_mfma_f32_16x16x32_bf16 v[44:47], v[132:135], v[226:229], v[44:47]
	v_mfma_f32_16x16x32_bf16 v[40:43], v[140:143], v[226:229], v[40:43]
	v_mfma_f32_16x16x32_bf16 v[28:31], v[132:135], v[234:237], v[28:31]
	v_mfma_f32_16x16x32_bf16 v[24:27], v[140:143], v[234:237], v[24:27]
	v_mfma_f32_16x16x32_bf16 v[12:15], v[132:135], v[242:245], v[12:15]
	v_mfma_f32_16x16x32_bf16 v[8:11], v[140:143], v[242:245], v[8:11]
	v_mfma_f32_16x16x32_bf16 v[52:55], v[174:177], v[214:217], v[52:55]
	v_mfma_f32_16x16x32_bf16 v[48:51], v[188:191], v[214:217], v[48:51]
	v_mfma_f32_16x16x32_bf16 v[36:39], v[174:177], v[222:225], v[36:39]
	v_mfma_f32_16x16x32_bf16 v[32:35], v[188:191], v[222:225], v[32:35]
	v_mfma_f32_16x16x32_bf16 v[20:23], v[174:177], v[230:233], v[20:23]
	v_mfma_f32_16x16x32_bf16 v[16:19], v[188:191], v[230:233], v[16:19]
	v_mfma_f32_16x16x32_bf16 v[4:7], v[174:177], v[238:241], v[4:7]
	v_mfma_f32_16x16x32_bf16 v[0:3], v[188:191], v[238:241], v[0:3]
	v_mfma_f32_16x16x32_bf16 v[52:55], v[184:187], v[218:221], v[52:55]
	v_mfma_f32_16x16x32_bf16 v[48:51], v[210:213], v[218:221], v[48:51]
	v_mfma_f32_16x16x32_bf16 v[36:39], v[184:187], v[226:229], v[36:39]
	v_mfma_f32_16x16x32_bf16 v[32:35], v[210:213], v[226:229], v[32:35]
	v_mfma_f32_16x16x32_bf16 v[20:23], v[184:187], v[234:237], v[20:23]
	v_mfma_f32_16x16x32_bf16 v[16:19], v[210:213], v[234:237], v[16:19]
	v_mfma_f32_16x16x32_bf16 v[4:7], v[184:187], v[242:245], v[4:7]
	v_mfma_f32_16x16x32_bf16 v[0:3], v[210:213], v[242:245], v[0:3]
	s_setprio 0
	s_barrier
	s_add_i32 s13, s13, 2
	s_add_u32 s10, s10, 0x100
	s_addc_u32 s11, s11, 0
	s_cmp_gt_u32 s13, 41
	s_mov_b64 s[0:1], s[2:3]
	s_cbranch_scc0 .LBB0_545
	s_and_b64 vcc, exec, s[22:23]
	s_cbranch_vccz .LBB0_548
	s_barrier
